# diff-attn v128 loop: 12 of 16 bf16 packs per step moved from the QK segment gaps into the PV segment gaps of the previous step; on top of f1
# baseline (speedup 1.0000x reference)
; __device__ __forceinline__ float fsub_s(float a,float b){float r;asm("v_sub_f32_e32 %0, %1, %2":"=v"(r):"v"(a),"v"(b));return r;}
; #define WAIT_BAR(N) asm volatile("s_waitcnt vmcnt(" #N ") lgkmcnt(0)\n\ts_barrier":::"memory")
;   #define DMA_K(t,slot) glds16(ksrc+(long)(t)*KVBLK*kp,(unsigned)__builtin_amdgcn_readfirstlane(kdst+(slot)))
;   #define DMA_V(t,slot) glds16(vsrc+(long)(t)*KVBLK*vp,(unsigned)__builtin_amdgcn_readfirstlane(vdst+(slot)))
; template<int THRL,bool NOMAX=false> __device__ __forceinline__ void attn_unit_v128(const bf16*Qu,int qp,const bf16*__restrict__ Kh,int kp,const bf16*__restrict__ Vh,int vp,bf16*Ou,int op,int NT,char*shm,int tid_in){
;   int tid_=tid_in; asm volatile("":"+v"(tid_));
;   const int tid=tid_,lane=tid&63,r32=lane&31,hi=lane>>5; const int wid=__builtin_amdgcn_readfirstlane(tid>>6);
;   const bf16*Qw=Qu+(long)(wid*QBLK)*qp;
;   const unsigned lds0=(unsigned)(uintptr_t)shm;
;   float*wsf=(float*)(shm+V2_LDS_WS)+wid*64;
;   const bf16*ksrc=Kh+(long)lane*kp+wid*8;
;   const bf16*vsrc=Vh+(long)(16*(wid&3)+(lane>>2))*vp+(wid>>2)*32+(lane&3)*8;
;   const unsigned kdst=lds0+V2_LDS_K+wid*1024, vdst=lds0+V2_LDS_V+wid*1024;
;     ...
;   const int vb0=(int)(lds0+V2_LDS_V)+((lane>>4)&1)*32+(lane&3)*8+(4*hi+((lane&15)>>2))*64;
;   const char*Kbase=shm+V2_LDS_K; bf16x8 kf[8];
;   const lds_cptr shm3=(lds_cptr)shm; const lds_cptr kp0=shm3+V2_LDS_K+hi*1024+r32*16; const lds_cptr vp0=shm3+V2_LDS_V+((lane>>4)&1)*32+(lane&3)*8+(4*hi+((lane&15)>>2))*64;
;   DMA_K(0,0);DMA_V(0,0);DMA_K(1,SLOTB);
;   bf16x8 qr[4];
;   #pragma unroll
;   for(int d0=0;d0<4;++d0)qr[d0]=*reinterpret_cast<const bf16x8*>(&Qw[(long)r32*qp+d0*16+hi*8]);
;   float mhat=0.f,l_reg=0.f;f32x16 o[4];o[0]=f32x16{};o[1]=f32x16{};o[2]=f32x16{};o[3]=f32x16{};
;   const f32x16 zero16=f32x16{};
;   bool resc=false;
;     ...
;   f32x16 pA0,pA1,pB0,pB1;
;   int sl_prev=0,sl_cur=0,sl_next=SLOTB;
;     ...
;   DMA_K(2,2*SLOTB);
;   WAIT_BAR(3);
;   qkt0(pA0,pA1,Kbase,qr,r32,hi);asm volatile("s_nop 15\n\ts_nop 7":"+v"(pA0),"+v"(pA1));
;   START(pA0,pA1);
;   if constexpr(NOMAX){ _Pragma("unroll") for(int r=0;r<16;++r)pA1[r]=__builtin_amdgcn_exp2f(pA1[r]); } else { _Pragma("unroll") for(int r=0;r<16;++r)pA1[r]=__builtin_amdgcn_exp2f(fsub_s(pA1[r],mhat)); }
;   WAIT_BAR(0);
;   DMA_K(3,0);DMA_V(1,SLOTB);
;   ROT();
;   kload8(kf,kp0+sl_cur);
;   WAIT_BAR(3);
.LBB0_795:
	s_and_b64 vcc, exec, s[6:7]
	s_cbranch_vccz .LBB0_839
	v_readlane_b32 s2, v253, 6
	v_mbcnt_lo_u32_b32 v0, -1, 0
	v_mbcnt_hi_u32_b32 v0, -1, v0
	s_mov_b32 s86, 1
	s_waitcnt vmcnt(7)
	v_or_b32_e32 v46, s2, v0
	s_nop 0
	v_readfirstlane_b32 s39, v46
	s_ashr_i32 s38, s39, 6
	s_lshl_b32 s2, s38, 5
	s_ashr_i32 s3, s2, 31
	s_lshl_b64 s[2:3], s[2:3], 10
	v_and_b32_e32 v206, 63, v46
	s_add_u32 s6, s33, s2
	s_addc_u32 s7, s76, s3
	v_lshrrev_b32_e32 v2, 3, v206
	v_lshl_add_u32 v2, s38, 3, v2
	v_lshrrev_b32_e32 v3, 1, v2
	v_xor_b32_e32 v3, v3, v206
	v_and_b32_e32 v3, 7, v3
	v_lshlrev_b32_e32 v2, 10, v2
	v_lshl_add_u32 v0, v3, 4, v2
	v_lshl_add_u64 v[194:195], s[36:37], 0, v[0:1]
	s_lshl_b32 s8, s38, 4
	v_bfe_u32 v0, v46, 2, 4
	v_and_or_b32 v0, s8, 48, v0
	s_ashr_i32 s8, s39, 3
	s_andn2_b32 s8, s8, 31
	v_lshlrev_b32_e32 v0, 10, v0
	s_ashr_i32 s9, s8, 31
	s_lshl_b32 s33, s38, 10
	v_lshl_add_u64 v[2:3], s[34:35], 0, v[0:1]
	v_lshlrev_b32_e32 v209, 3, v46
	s_cmp_lg_u32 0, -1
	v_lshl_add_u64 v[2:3], s[8:9], 1, v[2:3]
	v_and_b32_e32 v211, 24, v209
	s_cselect_b32 s8, 0, 0
	v_lshlrev_b32_e32 v0, 1, v211
	s_add_i32 s33, s33, s8
	s_mov_b32 s8, m0
	s_mov_b32 m0, s33
	s_nop 0
	global_load_lds_dwordx4 v[194:195], off
	s_mov_b32 m0, s8
	v_and_b32_e32 v207, 31, v46
	v_lshl_add_u64 v[196:197], v[2:3], 0, v[0:1]
	s_add_i32 s34, s33, 0x6000
	s_mov_b32 s8, m0
	s_mov_b32 m0, s34
	s_nop 0
	global_load_lds_dwordx4 v[196:197], off
	s_mov_b32 m0, s8
	v_bfe_u32 v208, v46, 5, 1
	v_lshl_add_u64 v[198:199], v[196:197], 0, s[0:1]
	s_add_i32 s8, s33, 0x8000
	s_mov_b32 s9, m0
	s_mov_b32 m0, s8
	s_nop 0
	global_load_lds_dwordx4 v[198:199], off
	s_mov_b32 m0, s9
	s_mov_b64 s[76:77], 0x10000
	v_lshlrev_b32_e32 v0, 10, v207
	v_lshl_add_u64 v[2:3], v[194:195], 0, s[76:77]
	s_add_i32 s8, s33, 0x2000
	s_mov_b32 s9, m0
	s_mov_b32 m0, s8
	s_nop 0
	global_load_lds_dwordx4 v[2:3], off
	s_mov_b32 m0, s9
	v_lshl_or_b32 v0, v208, 4, v0
	global_load_dwordx4 v[154:157], v0, s[6:7]
	global_load_dwordx4 v[150:153], v0, s[6:7] offset:32
	global_load_dwordx4 v[142:145], v0, s[6:7] offset:64
	global_load_dwordx4 v[134:137], v0, s[6:7] offset:96
	s_mov_b64 s[6:7], 0x20000
	v_lshlrev_b32_e32 v0, 7, v207
	v_bfe_u32 v2, v207, 2, 2
	v_lshl_add_u32 v0, v2, 5, v0
	v_bfe_u32 v2, v207, 1, 1
	v_xor_b32_e32 v2, v2, v208
	v_lshl_add_u32 v212, v2, 4, v0
	v_xor_b32_e32 v217, 32, v212
	v_xor_b32_e32 v218, 64, v212
	v_xor_b32_e32 v219, 0x60, v212
	v_lshl_add_u64 v[2:3], v[194:195], 0, s[6:7]
	s_add_i32 s6, s33, 0x4000
	s_mov_b32 s7, m0
	s_mov_b32 m0, s6
	s_nop 0
	global_load_lds_dwordx4 v[2:3], off
	s_mov_b32 m0, s7
	s_waitcnt vmcnt(3) lgkmcnt(0)
	s_barrier
	ds_read_b128 v[2:5], v212
	ds_read_b128 v[6:9], v212 offset:4096
	ds_read_b128 v[34:37], v217
	ds_read_b128 v[38:41], v217 offset:4096
	s_mov_b64 s[6:7], 0x30000
	v_lshlrev_b32_e32 v0, 1, v46
	v_and_b32_e32 v213, 32, v0
	s_mov_b32 s8, 0
	s_movk_i32 s35, 0x2000
	s_movk_i32 s36, 0x4000
	s_and_b64 vcc, exec, s[4:5]
	s_waitcnt vmcnt(3) lgkmcnt(3)
	v_mfma_f32_32x32x16_bf16 v[18:33], v[2:5], v[154:157], 0
	s_waitcnt lgkmcnt(2)
	v_mfma_f32_32x32x16_bf16 v[2:17], v[6:9], v[154:157], 0
	s_waitcnt vmcnt(2) lgkmcnt(1)
	v_mfma_f32_32x32x16_bf16 v[18:33], v[34:37], v[150:153], v[18:33]
	ds_read_b128 v[34:37], v218 offset:4096
	ds_read_b128 v[42:45], v218
	s_waitcnt lgkmcnt(2)
	v_mfma_f32_32x32x16_bf16 v[2:17], v[38:41], v[150:153], v[2:17]
	s_waitcnt vmcnt(1) lgkmcnt(0)
	v_mfma_f32_32x32x16_bf16 v[18:33], v[42:45], v[142:145], v[18:33]
	ds_read_b128 v[38:41], v219 offset:4096
	ds_read_b128 v[42:45], v219
	v_mfma_f32_32x32x16_bf16 v[2:17], v[34:37], v[142:145], v[2:17]
	v_lshlrev_b32_e32 v34, 4, v46
	v_and_b32_e32 v0, 0xc0, v34
	v_lshl_or_b32 v0, v208, 8, v0
	v_add_u32_e32 v34, 0, v213
	v_add3_u32 v214, v34, v211, v0
	s_waitcnt vmcnt(0) lgkmcnt(0)
	v_mfma_f32_32x32x16_bf16 v[18:33], v[42:45], v[134:137], v[18:33]
	v_mfma_f32_32x32x16_bf16 v[2:17], v[38:41], v[134:137], v[2:17]
	s_nop 15
	s_nop 7
	s_waitcnt vmcnt(0) lgkmcnt(0)
	s_barrier
	s_nop 10
	v_exp_f32_e32 v82, v18
	v_exp_f32_e32 v83, v19
	v_exp_f32_e32 v66, v2
	v_exp_f32_e32 v67, v3
	v_lshl_add_u64 v[2:3], v[194:195], 0, s[6:7]
	s_mov_b32 s6, m0
	s_mov_b32 m0, s33
	s_nop 0
	global_load_lds_dwordx4 v[2:3], off
	s_mov_b32 m0, s6
	v_lshl_add_u64 v[2:3], v[196:197], 0, s[76:77]
	s_add_i32 s6, s33, 0xa000
	s_mov_b32 s7, m0
	s_mov_b32 m0, s6
	s_nop 0
	global_load_lds_dwordx4 v[2:3], off
	s_mov_b32 m0, s7
	s_mov_b64 s[6:7], 0x10080
	v_lshl_add_u64 v[2:3], v[196:197], 0, s[6:7]
	s_add_i32 s6, s33, 0xc000
	s_mov_b32 s7, m0
	s_mov_b32 m0, s6
	s_nop 0
	global_load_lds_dwordx4 v[2:3], off
	s_mov_b32 m0, s7
	ds_read_b128 v[186:189], v212 offset:8192
	ds_read_b128 v[174:177], v212 offset:12288
	ds_read_b128 v[190:193], v217 offset:8192
	ds_read_b128 v[178:181], v217 offset:12288
	ds_read_b128 v[182:185], v218 offset:8192
	ds_read_b128 v[166:169], v218 offset:12288
	ds_read_b128 v[170:173], v219 offset:8192
	ds_read_b128 v[162:165], v219 offset:12288
	v_exp_f32_e32 v84, v20
	v_exp_f32_e32 v85, v21
	v_exp_f32_e32 v86, v22
	v_exp_f32_e32 v87, v23
	v_exp_f32_e32 v88, v24
	v_exp_f32_e32 v89, v25
	v_exp_f32_e32 v90, v26
	v_exp_f32_e32 v91, v27
	v_exp_f32_e32 v92, v28
	v_exp_f32_e32 v93, v29
	v_exp_f32_e32 v94, v30
	v_exp_f32_e32 v95, v31
	v_exp_f32_e32 v96, v32
	v_exp_f32_e32 v97, v33
	v_exp_f32_e32 v68, v4
	v_exp_f32_e32 v69, v5
	v_exp_f32_e32 v70, v6
	v_exp_f32_e32 v71, v7
	v_exp_f32_e32 v72, v8
	v_exp_f32_e32 v73, v9
	v_exp_f32_e32 v74, v10
	v_exp_f32_e32 v75, v11
	v_exp_f32_e32 v76, v12
	v_exp_f32_e32 v77, v13
	v_exp_f32_e32 v78, v14
	v_exp_f32_e32 v79, v15
	v_exp_f32_e32 v80, v16
	v_exp_f32_e32 v81, v17
	s_waitcnt vmcnt(3) lgkmcnt(0)
	s_barrier
; template<int THRL,bool NOMAX=false> __device__ __forceinline__ void attn_unit_v128(const bf16*Qu,int qp,const bf16*__restrict__ Kh,int kp,const bf16*__restrict__ Vh,int vp,bf16*Ou,int op,int NT,char*shm,int tid_in){
;     ...
;   float mhat=0.f,l_reg=0.f;f32x16 o[4];o[0]=f32x16{};o[1]=f32x16{};o[2]=f32x16{};o[3]=f32x16{};
	s_cbranch_vccnz .LBB0_800
	v_mov_b32_e32 v210, 0
	s_mov_b32 s9, 0
	s_mov_b32 s10, 6
	s_mov_b64 s[4:5], 0
	v_mov_b32_e32 v34, 0
	v_mov_b32_e32 v35, v210
	v_mov_b32_e32 v36, v210
	v_mov_b32_e32 v37, v210
	v_mov_b32_e32 v38, v210
	v_mov_b32_e32 v39, v210
	v_mov_b32_e32 v40, v210
	v_mov_b32_e32 v41, v210
	v_mov_b32_e32 v42, v210
	v_mov_b32_e32 v43, v210
	v_mov_b32_e32 v44, v210
	v_mov_b32_e32 v45, v210
	v_mov_b32_e32 v46, v210
	v_mov_b32_e32 v47, v210
	v_mov_b32_e32 v48, v210
	v_mov_b32_e32 v49, v210
	v_mov_b32_e32 v50, 0
	v_mov_b32_e32 v51, v210
	v_mov_b32_e32 v52, v210
	v_mov_b32_e32 v53, v210
	v_mov_b32_e32 v54, v210
	v_mov_b32_e32 v55, v210
	v_mov_b32_e32 v56, v210
	v_mov_b32_e32 v57, v210
	v_mov_b32_e32 v58, v210
	v_mov_b32_e32 v59, v210
	v_mov_b32_e32 v60, v210
	v_mov_b32_e32 v61, v210
	v_mov_b32_e32 v62, v210
	v_mov_b32_e32 v63, v210
	v_mov_b32_e32 v64, v210
	v_mov_b32_e32 v65, v210
	v_mov_b32_e32 v2, 0
	v_mov_b32_e32 v3, v210
	v_mov_b32_e32 v4, v210
	v_mov_b32_e32 v5, v210
	v_mov_b32_e32 v6, v210
	v_mov_b32_e32 v7, v210
	v_mov_b32_e32 v8, v210
	v_mov_b32_e32 v9, v210
	v_mov_b32_e32 v10, v210
	v_mov_b32_e32 v11, v210
	v_mov_b32_e32 v12, v210
	v_mov_b32_e32 v13, v210
	v_mov_b32_e32 v14, v210
	v_mov_b32_e32 v15, v210
	v_mov_b32_e32 v16, v210
	v_mov_b32_e32 v17, v210
	v_mov_b32_e32 v18, 0
	v_mov_b32_e32 v19, v210
	v_mov_b32_e32 v20, v210
	v_mov_b32_e32 v21, v210
	v_mov_b32_e32 v22, v210
	v_mov_b32_e32 v23, v210
	v_mov_b32_e32 v24, v210
	v_mov_b32_e32 v25, v210
	v_mov_b32_e32 v26, v210
	v_mov_b32_e32 v27, v210
	v_mov_b32_e32 v28, v210
	v_mov_b32_e32 v29, v210
	v_mov_b32_e32 v30, v210
	v_mov_b32_e32 v31, v210
	v_mov_b32_e32 v32, v210
	v_mov_b32_e32 v33, v210
	s_mov_b64 s[12:13], 0x40000
	s_mov_b64 s[14:15], 0x20000
	s_mov_b64 s[16:17], 0x30000
	s_mov_b64 s[18:19], 0x50000
	v_cvt_pk_bf16_f32 v158, v82, v83
	v_cvt_pk_bf16_f32 v159, v84, v85
	v_cvt_pk_bf16_f32 v160, v86, v87
	v_cvt_pk_bf16_f32 v161, v88, v89
	v_cvt_pk_bf16_f32 v146, v90, v91
	v_cvt_pk_bf16_f32 v147, v92, v93
	v_cvt_pk_bf16_f32 v148, v94, v95
	v_cvt_pk_bf16_f32 v149, v96, v97
	v_cvt_pk_bf16_f32 v138, v66, v67
	v_cvt_pk_bf16_f32 v139, v68, v69
	v_cvt_pk_bf16_f32 v140, v70, v71
	v_cvt_pk_bf16_f32 v141, v72, v73
.LBB0_798:
	s_mov_b32 s8, s36
	s_mov_b32 s6, s10
	s_mov_b32 s7, s35
	v_add_f32_e32 v98, v82, v83
	v_add_f32_e32 v98, v84, v98
	v_add_f32_e32 v98, v85, v98
	v_add_f32_e32 v98, v86, v98
	v_add_f32_e32 v98, v87, v98
	v_lshl_add_u32 v201, s9, 1, v214
	s_waitcnt lgkmcnt(7)
	v_mfma_f32_32x32x16_bf16 v[114:129], v[186:189], v[154:157], 0
	s_nop 0
	v_add_f32_e32 v82, v88, v98
	v_add_f32_e32 v82, v89, v82
	v_add_f32_e32 v82, v90, v82
	v_add_f32_e32 v82, v91, v82
	s_waitcnt lgkmcnt(6)
	v_mfma_f32_32x32x16_bf16 v[98:113], v[174:177], v[154:157], 0
	v_add_f32_e32 v82, v92, v82
	v_add_f32_e32 v82, v93, v82
	v_add_f32_e32 v82, v94, v82
	v_add_f32_e32 v86, v95, v82
	s_waitcnt lgkmcnt(5)
	v_mfma_f32_32x32x16_bf16 v[114:129], v[190:193], v[150:153], v[114:129]
	ds_read_b64_tr_b16 v[82:83], v201 offset:24576
	ds_read_b64_tr_b16 v[84:85], v201 offset:25088
	v_add_f32_e32 v86, v96, v86
	v_add_f32_e32 v86, v97, v86
	v_add_f32_e32 v86, v66, v86
	v_add_f32_e32 v90, v67, v86
	s_waitcnt lgkmcnt(6)
	v_mfma_f32_32x32x16_bf16 v[98:113], v[178:181], v[150:153], v[98:113]
	ds_read_b64_tr_b16 v[86:87], v201 offset:28672
	ds_read_b64_tr_b16 v[88:89], v201 offset:29184
	v_add_f32_e32 v90, v68, v90
	v_add_f32_e32 v90, v69, v90
	v_add_f32_e32 v90, v70, v90
	v_add_f32_e32 v90, v71, v90
	s_waitcnt lgkmcnt(7)
	v_mfma_f32_32x32x16_bf16 v[114:129], v[182:185], v[142:145], v[114:129]
	ds_read_b64_tr_b16 v[66:67], v201 offset:32768
	ds_read_b64_tr_b16 v[68:69], v201 offset:33280
	v_add_f32_e32 v90, v72, v90
	v_add_f32_e32 v90, v73, v90
	v_add_f32_e32 v90, v74, v90
	v_add_f32_e32 v90, v75, v90
	s_waitcnt lgkmcnt(8)
	v_mfma_f32_32x32x16_bf16 v[98:113], v[166:169], v[142:145], v[98:113]
	ds_read_b64_tr_b16 v[70:71], v201 offset:36864
	ds_read_b64_tr_b16 v[72:73], v201 offset:37376
	v_add_f32_e32 v90, v76, v90
	v_add_f32_e32 v90, v77, v90
	v_add_f32_e32 v90, v78, v90
	v_add_f32_e32 v90, v79, v90
	v_cvt_pk_bf16_f32 v130, v74, v75
	v_cvt_pk_bf16_f32 v131, v76, v77
	s_waitcnt lgkmcnt(9)
	v_mfma_f32_32x32x16_bf16 v[114:129], v[170:173], v[134:137], v[114:129]
	ds_read_b64_tr_b16 v[74:75], v201 offset:25600
	ds_read_b64_tr_b16 v[76:77], v201 offset:26112
	v_add_f32_e32 v90, v80, v90
	v_add_f32_e32 v90, v81, v90
	v_add_f32_e32 v200, 0, v90
	v_cvt_pk_bf16_f32 v132, v78, v79
	v_cvt_pk_bf16_f32 v133, v80, v81
	s_waitcnt lgkmcnt(10)
	v_mfma_f32_32x32x16_bf16 v[98:113], v[162:165], v[134:137], v[98:113]
	v_lshl_add_u64 v[162:163], v[194:195], 0, s[4:5]
	s_add_i32 s9, s35, s33
	v_lshl_add_u64 v[78:79], v[162:163], 0, s[12:13]
	s_mov_b32 s10, m0
	s_mov_b32 m0, s9
	s_nop 0
	global_load_lds_dwordx4 v[78:79], off
	s_mov_b32 m0, s10
	v_lshl_add_u64 v[164:165], v[196:197], 0, s[4:5]
	s_lshl_b32 s9, s36, 1
	v_lshl_add_u64 v[78:79], v[164:165], 0, s[14:15]
	s_add_i32 s9, s9, s34
	s_mov_b32 s10, m0
	s_mov_b32 m0, s9
	s_nop 0
	global_load_lds_dwordx4 v[78:79], off
	s_mov_b32 m0, s10
	v_lshl_add_u64 v[166:167], v[198:199], 0, s[4:5]
	v_lshl_add_u64 v[78:79], v[166:167], 0, s[14:15]
	s_addk_i32 s9, 0x2000
	s_mov_b32 s10, m0
	s_mov_b32 m0, s9
	s_nop 0
	global_load_lds_dwordx4 v[78:79], off
	s_mov_b32 m0, s10
	s_waitcnt lgkmcnt(8)
	v_mfma_f32_32x32x16_bf16 v[34:49], v[158:161], v[82:85], v[34:49]
	v_exp_f32_e32 v114, v114
	v_exp_f32_e32 v115, v115
	ds_read_b64_tr_b16 v[78:79], v201 offset:29696
	ds_read_b64_tr_b16 v[80:81], v201 offset:30208
	s_waitcnt lgkmcnt(8)
	v_mfma_f32_32x32x16_bf16 v[50:65], v[158:161], v[86:89], v[50:65]
	v_exp_f32_e32 v116, v116
	v_exp_f32_e32 v117, v117
	ds_read_b64_tr_b16 v[82:83], v201 offset:33792
	ds_read_b64_tr_b16 v[84:85], v201 offset:34304
	s_waitcnt lgkmcnt(8)
	v_mfma_f32_32x32x16_bf16 v[2:17], v[158:161], v[66:69], v[2:17]
	v_exp_f32_e32 v118, v118
	v_exp_f32_e32 v119, v119
	ds_read_b64_tr_b16 v[86:87], v201 offset:37888
	ds_read_b64_tr_b16 v[88:89], v201 offset:38400
	s_waitcnt lgkmcnt(8)
	v_mfma_f32_32x32x16_bf16 v[18:33], v[158:161], v[70:73], v[18:33]
	v_exp_f32_e32 v120, v120
	v_exp_f32_e32 v121, v121
	ds_read_b64_tr_b16 v[70:71], v201 offset:26624
	ds_read_b64_tr_b16 v[72:73], v201 offset:27136
	v_add_u32_e32 v94, s8, v212
	v_add_u32_e32 v220, s8, v217
	v_add_u32_e32 v221, s8, v218
	v_add_u32_e32 v222, s8, v219
	ds_read_b128 v[90:93], v94
	ds_read_b128 v[66:69], v94 offset:4096
	s_waitcnt lgkmcnt(10)
	v_mfma_f32_32x32x16_bf16 v[34:49], v[146:149], v[74:77], v[34:49]
	v_exp_f32_e32 v122, v122
	v_exp_f32_e32 v123, v123
	v_cvt_pk_bf16_f32 v158, v114, v115
	ds_read_b64_tr_b16 v[74:75], v201 offset:30720
	ds_read_b64_tr_b16 v[76:77], v201 offset:31232
	s_waitcnt lgkmcnt(10)
	v_mfma_f32_32x32x16_bf16 v[50:65], v[146:149], v[78:81], v[50:65]
	v_exp_f32_e32 v124, v124
	v_exp_f32_e32 v125, v125
	v_cvt_pk_bf16_f32 v159, v116, v117
	ds_read_b64_tr_b16 v[78:79], v201 offset:34816
	ds_read_b64_tr_b16 v[80:81], v201 offset:35328
	s_waitcnt lgkmcnt(10)
	v_mfma_f32_32x32x16_bf16 v[2:17], v[146:149], v[82:85], v[2:17]
	v_exp_f32_e32 v126, v126
	v_exp_f32_e32 v127, v127
	v_cvt_pk_bf16_f32 v160, v118, v119
	ds_read_b64_tr_b16 v[82:83], v201 offset:38912
	ds_read_b64_tr_b16 v[84:85], v201 offset:39424
	ds_read_b128 v[168:171], v220
	ds_read_b128 v[172:175], v220 offset:4096
	s_waitcnt lgkmcnt(12)
	v_mfma_f32_32x32x16_bf16 v[18:33], v[146:149], v[86:89], v[18:33]
	v_exp_f32_e32 v128, v128
	v_exp_f32_e32 v129, v129
	v_cvt_pk_bf16_f32 v161, v120, v121
	ds_read_b64_tr_b16 v[86:87], v201 offset:27648
	ds_read_b64_tr_b16 v[88:89], v201 offset:28160
	s_waitcnt lgkmcnt(12)
	v_mfma_f32_32x32x16_bf16 v[34:49], v[138:141], v[70:73], v[34:49]
	v_exp_f32_e32 v98, v98
	v_exp_f32_e32 v99, v99
	v_cvt_pk_bf16_f32 v146, v122, v123
	ds_read_b64_tr_b16 v[70:71], v201 offset:31744
	ds_read_b64_tr_b16 v[72:73], v201 offset:32256
	s_waitcnt lgkmcnt(10)
	v_mfma_f32_32x32x16_bf16 v[50:65], v[138:141], v[74:77], v[50:65]
	v_exp_f32_e32 v100, v100
	v_exp_f32_e32 v101, v101
	v_cvt_pk_bf16_f32 v147, v124, v125
	ds_read_b64_tr_b16 v[74:75], v201 offset:35840
	ds_read_b64_tr_b16 v[76:77], v201 offset:36352
	ds_read_b128 v[176:179], v221
	ds_read_b128 v[180:183], v221 offset:4096
	s_waitcnt lgkmcnt(12)
	v_mfma_f32_32x32x16_bf16 v[2:17], v[138:141], v[78:81], v[2:17]
	v_exp_f32_e32 v102, v102
	v_exp_f32_e32 v103, v103
	v_cvt_pk_bf16_f32 v148, v126, v127
	ds_read_b64_tr_b16 v[78:79], v201 offset:39936
	ds_read_b64_tr_b16 v[80:81], v201 offset:40448
	s_waitcnt lgkmcnt(12)
	v_mfma_f32_32x32x16_bf16 v[18:33], v[138:141], v[82:85], v[18:33]
	v_exp_f32_e32 v104, v104
	v_exp_f32_e32 v105, v105
	v_cvt_pk_bf16_f32 v149, v128, v129
	s_waitcnt lgkmcnt(8)
	v_mfma_f32_32x32x16_bf16 v[34:49], v[130:133], v[86:89], v[34:49]
	v_exp_f32_e32 v106, v106
	v_exp_f32_e32 v107, v107
	v_cvt_pk_bf16_f32 v138, v98, v99
	ds_read_b128 v[184:187], v222
	ds_read_b128 v[188:191], v222 offset:4096
	s_waitcnt lgkmcnt(8)
	v_mfma_f32_32x32x16_bf16 v[50:65], v[130:133], v[70:73], v[50:65]
	v_exp_f32_e32 v108, v108
	v_exp_f32_e32 v109, v109
	v_cvt_pk_bf16_f32 v139, v100, v101
	s_waitcnt lgkmcnt(6)
	v_mfma_f32_32x32x16_bf16 v[2:17], v[130:133], v[74:77], v[2:17]
	v_exp_f32_e32 v110, v110
	v_exp_f32_e32 v111, v111
	v_cvt_pk_bf16_f32 v140, v102, v103
	s_waitcnt lgkmcnt(2)
	v_mfma_f32_32x32x16_bf16 v[18:33], v[130:133], v[78:81], v[18:33]
	v_exp_f32_e32 v112, v112
	v_exp_f32_e32 v113, v113
	v_cvt_pk_bf16_f32 v141, v104, v105
	s_waitcnt vmcnt(3) lgkmcnt(0)
	s_barrier
	s_add_i32 s9, s36, 0x2000
	s_cmpk_lg_i32 s36, 0x4000
	s_cselect_b32 s35, s9, 0
	v_mfma_f32_32x32x16_bf16 v[82:97], v[90:93], v[154:157], 0
	v_add_f32_e32 v70, v114, v115
	v_add_f32_e32 v70, v116, v70
	v_add_f32_e32 v70, v117, v70
	v_add_f32_e32 v70, v118, v70
	v_add_f32_e32 v70, v119, v70
	v_lshl_add_u32 v201, s7, 1, v214
	s_nop 0
	v_add_f32_e32 v70, v120, v70
	v_add_f32_e32 v70, v121, v70
	v_add_f32_e32 v70, v122, v70
	v_add_f32_e32 v114, v123, v70
	v_mfma_f32_32x32x16_bf16 v[66:81], v[66:69], v[154:157], 0
	v_mfma_f32_32x32x16_bf16 v[82:97], v[168:171], v[150:153], v[82:97]
	v_add_f32_e32 v114, v124, v114
	v_add_f32_e32 v114, v125, v114
	v_add_f32_e32 v114, v126, v114
	v_add_f32_e32 v118, v127, v114
	ds_read_b64_tr_b16 v[114:115], v201 offset:24576
	ds_read_b64_tr_b16 v[116:117], v201 offset:25088
	v_mfma_f32_32x32x16_bf16 v[66:81], v[172:175], v[150:153], v[66:81]
	v_add_f32_e32 v118, v128, v118
	v_add_f32_e32 v118, v129, v118
	v_add_f32_e32 v118, v98, v118
	v_add_f32_e32 v122, v99, v118
	ds_read_b64_tr_b16 v[118:119], v201 offset:28672
	ds_read_b64_tr_b16 v[120:121], v201 offset:29184
	v_mfma_f32_32x32x16_bf16 v[82:97], v[176:179], v[142:145], v[82:97]
	v_add_f32_e32 v122, v100, v122
	v_add_f32_e32 v122, v101, v122
	v_add_f32_e32 v122, v102, v122
	v_add_f32_e32 v122, v103, v122
	ds_read_b64_tr_b16 v[98:99], v201 offset:32768
	ds_read_b64_tr_b16 v[100:101], v201 offset:33280
	v_mfma_f32_32x32x16_bf16 v[66:81], v[180:183], v[142:145], v[66:81]
	v_add_f32_e32 v122, v104, v122
	v_add_f32_e32 v122, v105, v122
	v_add_f32_e32 v122, v106, v122
	v_add_f32_e32 v122, v107, v122
	ds_read_b64_tr_b16 v[102:103], v201 offset:36864
	ds_read_b64_tr_b16 v[104:105], v201 offset:37376
	s_waitcnt lgkmcnt(9)
; #define WAIT_BAR(N) asm volatile("s_waitcnt vmcnt(" #N ") lgkmcnt(0)\n\ts_barrier":::"memory")
;   #define RESC() do{ if(resc){ asm volatile("s_waitcnt lgkmcnt(0)":::"memory"); \
;       _Pragma("unroll") for(int d_=0;d_<2;++d_) _Pragma("unroll") for(int r=0;r<16;++r)o[d_][r]*=wsf[crow(r,hi)]; } }while(0)
;   #define ROT() do{sl_prev=sl_cur;sl_cur=sl_next;sl_next=(sl_next==(NSLOT-1)*SLOTB)?0:sl_next+SLOTB;}while(0)
;   #define RESC() do{ if(resc){ asm volatile("s_waitcnt lgkmcnt(0)":::"memory"); \
;       _Pragma("unroll") for(int d_=0;d_<4;++d_) _Pragma("unroll") for(int r=0;r<16;++r)o[d_][r]*=wsf[crow(r,hi)]; } }while(0)
;   #define ROT() do{sl_prev=sl_cur;sl_cur=sl_next;sl_next=(sl_next==(NSLOT-1)*SLOTB)?0:sl_next+SLOTB;}while(0)
; template<int THRL,bool NOMAX=false> __device__ __forceinline__ void attn_unit_v128(const bf16*Qu,int qp,const bf16*__restrict__ Kh,int kp,const bf16*__restrict__ Vh,int vp,bf16*Ou,int op,int NT,char*shm,int tid_in){
;     ...
;   int t=1;
;   for(;t+5<NT;t+=2){
;     STEP(pB0,pB1,pA0,pA1,t,true,true,true);     WAIT_BAR(3); RESC(); ROT();
;     STEP(pA0,pA1,pB0,pB1,t+1,true,true,true);   WAIT_BAR(3); RESC(); ROT();
;   }
	v_mfma_f32_32x32x16_bf16 v[82:97], v[184:187], v[134:137], v[82:97]
	v_add_f32_e32 v122, v108, v122
	v_add_f32_e32 v122, v109, v122
	v_add_f32_e32 v122, v110, v122
	v_add_f32_e32 v122, v111, v122
	v_cvt_pk_bf16_f32 v130, v106, v107
	v_cvt_pk_bf16_f32 v131, v108, v109
	ds_read_b64_tr_b16 v[106:107], v201 offset:25600
	ds_read_b64_tr_b16 v[108:109], v201 offset:26112
	s_waitcnt lgkmcnt(10)
	v_mfma_f32_32x32x16_bf16 v[66:81], v[188:191], v[134:137], v[66:81]
	v_add_f32_e32 v122, v112, v122
	v_add_f32_e32 v122, v113, v122
	v_add_f32_e32 v122, 0, v122
	v_cvt_pk_bf16_f32 v132, v110, v111
	v_cvt_pk_bf16_f32 v133, v112, v113
	s_add_i32 s7, s36, s33
	v_lshl_add_u64 v[110:111], v[162:163], 0, s[18:19]
	s_mov_b32 s9, m0
	s_mov_b32 m0, s7
	s_nop 0
	global_load_lds_dwordx4 v[110:111], off
	s_mov_b32 m0, s9
	s_lshl_b32 s7, s35, 1
	v_lshl_add_u64 v[110:111], v[164:165], 0, s[16:17]
	s_add_i32 s7, s7, s34
	s_mov_b32 s9, m0
	s_mov_b32 m0, s7
	s_nop 0
	global_load_lds_dwordx4 v[110:111], off
	s_mov_b32 m0, s9
	v_lshl_add_u64 v[110:111], v[166:167], 0, s[16:17]
	s_addk_i32 s7, 0x2000
	s_mov_b32 s9, m0
	s_mov_b32 m0, s7
	s_nop 0
	global_load_lds_dwordx4 v[110:111], off
	s_mov_b32 m0, s9
	s_waitcnt lgkmcnt(8)
	v_mfma_f32_32x32x16_bf16 v[34:49], v[158:161], v[114:117], v[34:49]
	v_exp_f32_e32 v82, v82
	v_exp_f32_e32 v83, v83
	ds_read_b64_tr_b16 v[110:111], v201 offset:29696
	ds_read_b64_tr_b16 v[112:113], v201 offset:30208
	s_waitcnt lgkmcnt(8)
	v_mfma_f32_32x32x16_bf16 v[50:65], v[158:161], v[118:121], v[50:65]
	v_exp_f32_e32 v84, v84
	v_exp_f32_e32 v85, v85
	ds_read_b64_tr_b16 v[114:115], v201 offset:33792
	ds_read_b64_tr_b16 v[116:117], v201 offset:34304
	s_waitcnt lgkmcnt(8)
	v_mfma_f32_32x32x16_bf16 v[2:17], v[158:161], v[98:101], v[2:17]
	v_exp_f32_e32 v86, v86
	v_exp_f32_e32 v87, v87
	ds_read_b64_tr_b16 v[98:99], v201 offset:37888
	ds_read_b64_tr_b16 v[100:101], v201 offset:38400
	s_waitcnt lgkmcnt(8)
	v_mfma_f32_32x32x16_bf16 v[18:33], v[158:161], v[102:105], v[18:33]
	v_exp_f32_e32 v88, v88
	v_exp_f32_e32 v89, v89
	ds_read_b64_tr_b16 v[102:103], v201 offset:26624
	ds_read_b64_tr_b16 v[104:105], v201 offset:27136
	v_add_u32_e32 v118, s35, v212
	v_add_u32_e32 v220, s35, v217
	v_add_u32_e32 v221, s35, v218
	v_add_u32_e32 v222, s35, v219
	ds_read_b128 v[186:189], v118
	ds_read_b128 v[174:177], v118 offset:4096
	s_waitcnt lgkmcnt(10)
	v_mfma_f32_32x32x16_bf16 v[34:49], v[146:149], v[106:109], v[34:49]
	v_exp_f32_e32 v90, v90
	v_exp_f32_e32 v91, v91
	v_cvt_pk_bf16_f32 v158, v82, v83
	ds_read_b64_tr_b16 v[106:107], v201 offset:30720
	ds_read_b64_tr_b16 v[108:109], v201 offset:31232
	s_waitcnt lgkmcnt(10)
	v_mfma_f32_32x32x16_bf16 v[50:65], v[146:149], v[110:113], v[50:65]
	v_exp_f32_e32 v92, v92
	v_exp_f32_e32 v93, v93
	v_cvt_pk_bf16_f32 v159, v84, v85
	ds_read_b64_tr_b16 v[110:111], v201 offset:34816
	ds_read_b64_tr_b16 v[112:113], v201 offset:35328
	s_waitcnt lgkmcnt(10)
	v_mfma_f32_32x32x16_bf16 v[2:17], v[146:149], v[114:117], v[2:17]
	v_exp_f32_e32 v94, v94
	v_exp_f32_e32 v95, v95
	v_cvt_pk_bf16_f32 v160, v86, v87
	ds_read_b64_tr_b16 v[114:115], v201 offset:38912
	ds_read_b64_tr_b16 v[116:117], v201 offset:39424
	ds_read_b128 v[190:193], v220
	ds_read_b128 v[178:181], v220 offset:4096
	s_waitcnt lgkmcnt(12)
	v_mfma_f32_32x32x16_bf16 v[18:33], v[146:149], v[98:101], v[18:33]
	v_exp_f32_e32 v96, v96
	v_exp_f32_e32 v97, v97
	v_cvt_pk_bf16_f32 v161, v88, v89
	ds_read_b64_tr_b16 v[98:99], v201 offset:27648
	ds_read_b64_tr_b16 v[100:101], v201 offset:28160
	s_waitcnt lgkmcnt(12)
	v_mfma_f32_32x32x16_bf16 v[34:49], v[138:141], v[102:105], v[34:49]
	v_exp_f32_e32 v66, v66
	v_exp_f32_e32 v67, v67
	v_cvt_pk_bf16_f32 v146, v90, v91
	ds_read_b64_tr_b16 v[102:103], v201 offset:31744
	ds_read_b64_tr_b16 v[104:105], v201 offset:32256
	s_waitcnt lgkmcnt(10)
	v_mfma_f32_32x32x16_bf16 v[50:65], v[138:141], v[106:109], v[50:65]
	v_exp_f32_e32 v68, v68
	v_exp_f32_e32 v69, v69
	v_cvt_pk_bf16_f32 v147, v92, v93
	ds_read_b64_tr_b16 v[106:107], v201 offset:35840
	ds_read_b64_tr_b16 v[108:109], v201 offset:36352
	ds_read_b128 v[182:185], v221
	ds_read_b128 v[166:169], v221 offset:4096
	s_waitcnt lgkmcnt(12)
	v_mfma_f32_32x32x16_bf16 v[2:17], v[138:141], v[110:113], v[2:17]
	v_exp_f32_e32 v70, v70
	v_exp_f32_e32 v71, v71
	v_cvt_pk_bf16_f32 v148, v94, v95
	ds_read_b64_tr_b16 v[110:111], v201 offset:39936
	ds_read_b64_tr_b16 v[112:113], v201 offset:40448
	s_waitcnt lgkmcnt(12)
	v_mfma_f32_32x32x16_bf16 v[18:33], v[138:141], v[114:117], v[18:33]
	v_exp_f32_e32 v72, v72
	v_exp_f32_e32 v73, v73
	v_cvt_pk_bf16_f32 v149, v96, v97
	s_waitcnt lgkmcnt(8)
	v_mfma_f32_32x32x16_bf16 v[34:49], v[130:133], v[98:101], v[34:49]
	v_exp_f32_e32 v74, v74
	v_exp_f32_e32 v75, v75
	v_cvt_pk_bf16_f32 v138, v66, v67
	ds_read_b128 v[170:173], v222
	ds_read_b128 v[162:165], v222 offset:4096
	s_waitcnt lgkmcnt(8)
	v_mfma_f32_32x32x16_bf16 v[50:65], v[130:133], v[102:105], v[50:65]
	v_exp_f32_e32 v76, v76
	v_exp_f32_e32 v77, v77
	v_cvt_pk_bf16_f32 v139, v68, v69
	s_waitcnt lgkmcnt(6)
	v_mfma_f32_32x32x16_bf16 v[2:17], v[130:133], v[106:109], v[2:17]
	v_exp_f32_e32 v78, v78
	v_exp_f32_e32 v79, v79
	v_cvt_pk_bf16_f32 v140, v70, v71
	s_waitcnt lgkmcnt(2)
	v_mfma_f32_32x32x16_bf16 v[18:33], v[130:133], v[110:113], v[18:33]
	v_exp_f32_e32 v80, v80
	v_exp_f32_e32 v81, v81
	v_cvt_pk_bf16_f32 v141, v72, v73
	s_add_i32 s7, s35, 0x2000
	s_cmpk_lg_i32 s35, 0x4000
	s_mov_b32 s9, s36
	s_cselect_b32 s36, s7, 0
	s_add_i32 s10, s6, 2
	s_waitcnt vmcnt(3) lgkmcnt(0)
	s_barrier
	s_add_u32 s4, s4, 0x20000
	v_add_f32_e32 v98, v210, v200
	s_addc_u32 s5, s5, 0
	s_cmp_ge_u32 s10, s75
	v_add_f32_e32 v210, v98, v122
	s_cbranch_scc0 .LBB0_798
	s_add_i32 s86, s6, -3
	s_add_i32 s4, s86, 1
	s_cmp_ge_u32 s4, s75
	s_mov_b64 s[4:5], -1
	s_cbranch_scc0 .LBB0_802
	s_branch .LBB0_801
